# GEMM K-loops: scalar-base LDS-DMA; 6-load segments re-emitted as m0/ds_read/load triples (no s_nop separators); setprio raised before the pre-MFMA barrier, lowered after the post-MFMA barrier
# baseline (speedup 1.0000x reference)
.LBB0_126:
	ds_read_b128 v[130:133], v176
	ds_read_b128 v[134:137], v176 offset:1024
	ds_read_b128 v[170:173], v176 offset:2048
	ds_read_b128 v[180:183], v176 offset:3072
	ds_read_b128 v[184:187], v177
	ds_read_b128 v[188:191], v177 offset:1024
	ds_read_b128 v[192:195], v177 offset:2048
	ds_read_b128 v[198:201], v177 offset:3072
	s_add_u32 s14, s8, 0xfff00080
	s_addc_u32 s15, s9, -1
	s_cmp_eq_u32 s29, 60
	s_cselect_b32 s19, s11, s15
	s_cselect_b32 s18, s13, s14
	s_cselect_b32 s15, s17, s28
	s_cselect_b32 s14, s20, s21
	s_add_i32 m0, s73, 0xc000
	ds_read_b128 v[202:205], v178
	ds_read_b128 v[206:209], v178 offset:1024
	ds_read_b128 v[210:213], v178 offset:2048
	ds_read_b128 v[214:217], v178 offset:3072
	ds_read_b128 v[218:221], v178 offset:4096
	ds_read_b128 v[222:225], v178 offset:5120
	ds_read_b128 v[226:229], v178 offset:6144
	ds_read_b128 v[230:233], v178 offset:7168
	global_load_lds_dwordx4 v160, s[8:9]
	s_add_i32 m0, s73, 0xe000
	s_nop 0
	global_load_lds_dwordx4 v162, s[8:9]
	s_waitcnt vmcnt(8)
	s_waitcnt lgkmcnt(0)
	s_setprio 1
	s_barrier
	v_mfma_f32_16x16x32_bf16 v[126:129], v[130:133], v[202:205], v[126:129]
	v_mfma_f32_16x16x32_bf16 v[122:125], v[170:173], v[202:205], v[122:125]
	v_mfma_f32_16x16x32_bf16 v[110:113], v[130:133], v[210:213], v[110:113]
	v_mfma_f32_16x16x32_bf16 v[106:109], v[170:173], v[210:213], v[106:109]
	v_mfma_f32_16x16x32_bf16 v[94:97], v[130:133], v[218:221], v[94:97]
	v_mfma_f32_16x16x32_bf16 v[90:93], v[170:173], v[218:221], v[90:93]
	v_mfma_f32_16x16x32_bf16 v[78:81], v[130:133], v[226:229], v[78:81]
	v_mfma_f32_16x16x32_bf16 v[74:77], v[170:173], v[226:229], v[74:77]
	v_mfma_f32_16x16x32_bf16 v[126:129], v[134:137], v[206:209], v[126:129]
	v_mfma_f32_16x16x32_bf16 v[122:125], v[180:183], v[206:209], v[122:125]
	v_mfma_f32_16x16x32_bf16 v[110:113], v[134:137], v[214:217], v[110:113]
	v_mfma_f32_16x16x32_bf16 v[106:109], v[180:183], v[214:217], v[106:109]
	v_mfma_f32_16x16x32_bf16 v[94:97], v[134:137], v[222:225], v[94:97]
	v_mfma_f32_16x16x32_bf16 v[90:93], v[180:183], v[222:225], v[90:93]
	v_mfma_f32_16x16x32_bf16 v[78:81], v[134:137], v[230:233], v[78:81]
	v_mfma_f32_16x16x32_bf16 v[74:77], v[180:183], v[230:233], v[74:77]
	v_mfma_f32_16x16x32_bf16 v[118:121], v[184:187], v[202:205], v[118:121]
	v_mfma_f32_16x16x32_bf16 v[114:117], v[192:195], v[202:205], v[114:117]
	v_mfma_f32_16x16x32_bf16 v[102:105], v[184:187], v[210:213], v[102:105]
	v_mfma_f32_16x16x32_bf16 v[98:101], v[192:195], v[210:213], v[98:101]
	v_mfma_f32_16x16x32_bf16 v[86:89], v[184:187], v[218:221], v[86:89]
	v_mfma_f32_16x16x32_bf16 v[82:85], v[192:195], v[218:221], v[82:85]
	v_mfma_f32_16x16x32_bf16 v[70:73], v[184:187], v[226:229], v[70:73]
	v_mfma_f32_16x16x32_bf16 v[66:69], v[192:195], v[226:229], v[66:69]
	v_mfma_f32_16x16x32_bf16 v[118:121], v[188:191], v[206:209], v[118:121]
	v_mfma_f32_16x16x32_bf16 v[114:117], v[198:201], v[206:209], v[114:117]
	v_mfma_f32_16x16x32_bf16 v[102:105], v[188:191], v[214:217], v[102:105]
	v_mfma_f32_16x16x32_bf16 v[98:101], v[198:201], v[214:217], v[98:101]
	v_mfma_f32_16x16x32_bf16 v[86:89], v[188:191], v[222:225], v[86:89]
	v_mfma_f32_16x16x32_bf16 v[82:85], v[198:201], v[222:225], v[82:85]
	v_mfma_f32_16x16x32_bf16 v[70:73], v[188:191], v[230:233], v[70:73]
	v_mfma_f32_16x16x32_bf16 v[66:69], v[198:201], v[230:233], v[66:69]
	s_barrier
	s_setprio 0
	s_add_u32 s30, s14, 0x100000
	s_addc_u32 s31, s15, 0
	s_add_i32 m0, s35, 0x10000
	ds_read_b128 v[202:205], v178 offset:16384
	global_load_lds_dwordx4 v140, s[14:15]
	s_add_i32 m0, s35, 0x12000
	ds_read_b128 v[206:209], v178 offset:17408
	global_load_lds_dwordx4 v144, s[14:15]
	s_add_i32 m0, s35, 0x14000
	ds_read_b128 v[210:213], v178 offset:18432
	global_load_lds_dwordx4 v140, s[30:31]
	s_add_i32 m0, s35, 0x16000
	ds_read_b128 v[214:217], v178 offset:19456
	global_load_lds_dwordx4 v144, s[30:31]
	s_add_i32 m0, s35, 0x0
	ds_read_b128 v[218:221], v178 offset:20480
	global_load_lds_dwordx4 v138, s[18:19]
	s_add_i32 m0, s35, 0x2000
	ds_read_b128 v[222:225], v178 offset:21504
	global_load_lds_dwordx4 v142, s[18:19]
	ds_read_b128 v[226:229], v178 offset:22528
	ds_read_b128 v[230:233], v178 offset:23552
	s_waitcnt vmcnt(8)
	s_waitcnt lgkmcnt(0)
	s_setprio 1
	s_barrier
	v_mfma_f32_16x16x32_bf16 v[62:65], v[130:133], v[202:205], v[62:65]
	v_mfma_f32_16x16x32_bf16 v[58:61], v[170:173], v[202:205], v[58:61]
	v_mfma_f32_16x16x32_bf16 v[46:49], v[130:133], v[210:213], v[46:49]
	v_mfma_f32_16x16x32_bf16 v[42:45], v[170:173], v[210:213], v[42:45]
	v_mfma_f32_16x16x32_bf16 v[30:33], v[130:133], v[218:221], v[30:33]
	v_mfma_f32_16x16x32_bf16 v[26:29], v[170:173], v[218:221], v[26:29]
	v_mfma_f32_16x16x32_bf16 v[14:17], v[130:133], v[226:229], v[14:17]
	v_mfma_f32_16x16x32_bf16 v[10:13], v[170:173], v[226:229], v[10:13]
	v_mfma_f32_16x16x32_bf16 v[62:65], v[134:137], v[206:209], v[62:65]
	v_mfma_f32_16x16x32_bf16 v[58:61], v[180:183], v[206:209], v[58:61]
	v_mfma_f32_16x16x32_bf16 v[46:49], v[134:137], v[214:217], v[46:49]
	v_mfma_f32_16x16x32_bf16 v[42:45], v[180:183], v[214:217], v[42:45]
	v_mfma_f32_16x16x32_bf16 v[30:33], v[134:137], v[222:225], v[30:33]
	v_mfma_f32_16x16x32_bf16 v[26:29], v[180:183], v[222:225], v[26:29]
	v_mfma_f32_16x16x32_bf16 v[14:17], v[134:137], v[230:233], v[14:17]
	v_mfma_f32_16x16x32_bf16 v[10:13], v[180:183], v[230:233], v[10:13]
	v_mfma_f32_16x16x32_bf16 v[54:57], v[184:187], v[202:205], v[54:57]
	v_mfma_f32_16x16x32_bf16 v[50:53], v[192:195], v[202:205], v[50:53]
	v_mfma_f32_16x16x32_bf16 v[38:41], v[184:187], v[210:213], v[38:41]
	v_mfma_f32_16x16x32_bf16 v[34:37], v[192:195], v[210:213], v[34:37]
	v_mfma_f32_16x16x32_bf16 v[22:25], v[184:187], v[218:221], v[22:25]
	v_mfma_f32_16x16x32_bf16 v[18:21], v[192:195], v[218:221], v[18:21]
	v_mfma_f32_16x16x32_bf16 v[6:9], v[184:187], v[226:229], v[6:9]
	v_mfma_f32_16x16x32_bf16 v[2:5], v[192:195], v[226:229], v[2:5]
	v_mfma_f32_16x16x32_bf16 v[54:57], v[188:191], v[206:209], v[54:57]
	v_mfma_f32_16x16x32_bf16 v[50:53], v[198:201], v[206:209], v[50:53]
	v_mfma_f32_16x16x32_bf16 v[38:41], v[188:191], v[214:217], v[38:41]
	v_mfma_f32_16x16x32_bf16 v[34:37], v[198:201], v[214:217], v[34:37]
	v_mfma_f32_16x16x32_bf16 v[22:25], v[188:191], v[222:225], v[22:25]
	v_mfma_f32_16x16x32_bf16 v[18:21], v[198:201], v[222:225], v[18:21]
	v_mfma_f32_16x16x32_bf16 v[6:9], v[188:191], v[230:233], v[6:9]
	v_mfma_f32_16x16x32_bf16 v[2:5], v[198:201], v[230:233], v[2:5]
	s_barrier
	s_setprio 0
	s_add_i32 s30, 0, 0x18000
	v_add_u32_e32 v146, s30, v155
	s_add_i32 s31, 0, 0x1c000
	ds_read_b128 v[130:133], v146
	ds_read_b128 v[134:137], v146 offset:1024
	ds_read_b128 v[170:173], v146 offset:2048
	ds_read_b128 v[180:183], v146 offset:3072
	v_add_u32_e32 v146, s31, v155
	ds_read_b128 v[184:187], v146
	ds_read_b128 v[188:191], v146 offset:1024
	ds_read_b128 v[192:195], v146 offset:2048
	ds_read_b128 v[198:201], v146 offset:3072
	s_add_u32 s18, s18, 0x100000
	s_addc_u32 s19, s19, 0
	s_mov_b32 m0, s67
	ds_read_b128 v[202:205], v178 offset:32768
	ds_read_b128 v[206:209], v178 offset:33792
	ds_read_b128 v[210:213], v178 offset:34816
	ds_read_b128 v[214:217], v178 offset:35840
	ds_read_b128 v[218:221], v178 offset:36864
	ds_read_b128 v[222:225], v178 offset:37888
	ds_read_b128 v[226:229], v178 offset:38912
	ds_read_b128 v[230:233], v178 offset:39936
	global_load_lds_dwordx4 v138, s[18:19]
	s_mov_b32 m0, s88
	s_nop 0
	global_load_lds_dwordx4 v142, s[18:19]
	s_waitcnt vmcnt(8)
	s_waitcnt lgkmcnt(0)
	s_setprio 1
	s_barrier
	v_mfma_f32_16x16x32_bf16 v[126:129], v[130:133], v[202:205], v[126:129]
	v_mfma_f32_16x16x32_bf16 v[122:125], v[170:173], v[202:205], v[122:125]
	v_mfma_f32_16x16x32_bf16 v[110:113], v[130:133], v[210:213], v[110:113]
	v_mfma_f32_16x16x32_bf16 v[106:109], v[170:173], v[210:213], v[106:109]
	v_mfma_f32_16x16x32_bf16 v[94:97], v[130:133], v[218:221], v[94:97]
	v_mfma_f32_16x16x32_bf16 v[90:93], v[170:173], v[218:221], v[90:93]
	v_mfma_f32_16x16x32_bf16 v[78:81], v[130:133], v[226:229], v[78:81]
	v_mfma_f32_16x16x32_bf16 v[74:77], v[170:173], v[226:229], v[74:77]
	v_mfma_f32_16x16x32_bf16 v[126:129], v[134:137], v[206:209], v[126:129]
	v_mfma_f32_16x16x32_bf16 v[122:125], v[180:183], v[206:209], v[122:125]
	v_mfma_f32_16x16x32_bf16 v[110:113], v[134:137], v[214:217], v[110:113]
	v_mfma_f32_16x16x32_bf16 v[106:109], v[180:183], v[214:217], v[106:109]
	v_mfma_f32_16x16x32_bf16 v[94:97], v[134:137], v[222:225], v[94:97]
	v_mfma_f32_16x16x32_bf16 v[90:93], v[180:183], v[222:225], v[90:93]
	v_mfma_f32_16x16x32_bf16 v[78:81], v[134:137], v[230:233], v[78:81]
	v_mfma_f32_16x16x32_bf16 v[74:77], v[180:183], v[230:233], v[74:77]
	v_mfma_f32_16x16x32_bf16 v[118:121], v[184:187], v[202:205], v[118:121]
	v_mfma_f32_16x16x32_bf16 v[114:117], v[192:195], v[202:205], v[114:117]
	v_mfma_f32_16x16x32_bf16 v[102:105], v[184:187], v[210:213], v[102:105]
	v_mfma_f32_16x16x32_bf16 v[98:101], v[192:195], v[210:213], v[98:101]
	v_mfma_f32_16x16x32_bf16 v[86:89], v[184:187], v[218:221], v[86:89]
	v_mfma_f32_16x16x32_bf16 v[82:85], v[192:195], v[218:221], v[82:85]
	v_mfma_f32_16x16x32_bf16 v[70:73], v[184:187], v[226:229], v[70:73]
	v_mfma_f32_16x16x32_bf16 v[66:69], v[192:195], v[226:229], v[66:69]
	v_mfma_f32_16x16x32_bf16 v[118:121], v[188:191], v[206:209], v[118:121]
	v_mfma_f32_16x16x32_bf16 v[114:117], v[198:201], v[206:209], v[114:117]
	v_mfma_f32_16x16x32_bf16 v[102:105], v[188:191], v[214:217], v[102:105]
	v_mfma_f32_16x16x32_bf16 v[98:101], v[198:201], v[214:217], v[98:101]
	v_mfma_f32_16x16x32_bf16 v[86:89], v[188:191], v[222:225], v[86:89]
	v_mfma_f32_16x16x32_bf16 v[82:85], v[198:201], v[222:225], v[82:85]
	v_mfma_f32_16x16x32_bf16 v[70:73], v[188:191], v[230:233], v[70:73]
	v_mfma_f32_16x16x32_bf16 v[66:69], v[198:201], v[230:233], v[66:69]
	s_barrier
	s_setprio 0
	s_add_u32 s14, s14, 0x80
	s_addc_u32 s15, s15, 0
	s_add_u32 s30, s14, 0x100000
	s_addc_u32 s31, s15, 0
	s_add_u32 s18, s18, 0xfff00080
	s_addc_u32 s19, s19, -1
	s_add_i32 m0, s35, 0x18000
	ds_read_b128 v[202:205], v178 offset:49152
	global_load_lds_dwordx4 v140, s[14:15]
	s_add_i32 m0, s35, 0x1a000
	ds_read_b128 v[206:209], v178 offset:50176
	global_load_lds_dwordx4 v144, s[14:15]
	s_add_i32 m0, s35, 0x1c000
	ds_read_b128 v[210:213], v178 offset:51200
	global_load_lds_dwordx4 v140, s[30:31]
	s_add_i32 m0, s35, 0x1e000
	ds_read_b128 v[214:217], v178 offset:52224
	global_load_lds_dwordx4 v144, s[30:31]
	s_add_i32 m0, s35, 0x8000
	ds_read_b128 v[218:221], v178 offset:53248
	global_load_lds_dwordx4 v138, s[18:19]
	s_add_i32 m0, s35, 0xa000
	ds_read_b128 v[222:225], v178 offset:54272
	global_load_lds_dwordx4 v142, s[18:19]
	ds_read_b128 v[226:229], v178 offset:55296
	ds_read_b128 v[230:233], v178 offset:56320
	s_waitcnt vmcnt(8)
	s_waitcnt lgkmcnt(0)
	s_setprio 1
	s_barrier
	v_mfma_f32_16x16x32_bf16 v[62:65], v[130:133], v[202:205], v[62:65]
	v_mfma_f32_16x16x32_bf16 v[58:61], v[170:173], v[202:205], v[58:61]
	v_mfma_f32_16x16x32_bf16 v[46:49], v[130:133], v[210:213], v[46:49]
	v_mfma_f32_16x16x32_bf16 v[42:45], v[170:173], v[210:213], v[42:45]
	v_mfma_f32_16x16x32_bf16 v[30:33], v[130:133], v[218:221], v[30:33]
	v_mfma_f32_16x16x32_bf16 v[26:29], v[170:173], v[218:221], v[26:29]
	v_mfma_f32_16x16x32_bf16 v[14:17], v[130:133], v[226:229], v[14:17]
	v_mfma_f32_16x16x32_bf16 v[10:13], v[170:173], v[226:229], v[10:13]
	v_mfma_f32_16x16x32_bf16 v[62:65], v[134:137], v[206:209], v[62:65]
	v_mfma_f32_16x16x32_bf16 v[58:61], v[180:183], v[206:209], v[58:61]
	v_mfma_f32_16x16x32_bf16 v[46:49], v[134:137], v[214:217], v[46:49]
	v_mfma_f32_16x16x32_bf16 v[42:45], v[180:183], v[214:217], v[42:45]
	v_mfma_f32_16x16x32_bf16 v[30:33], v[134:137], v[222:225], v[30:33]
	v_mfma_f32_16x16x32_bf16 v[26:29], v[180:183], v[222:225], v[26:29]
	v_mfma_f32_16x16x32_bf16 v[14:17], v[134:137], v[230:233], v[14:17]
	v_mfma_f32_16x16x32_bf16 v[10:13], v[180:183], v[230:233], v[10:13]
	v_mfma_f32_16x16x32_bf16 v[54:57], v[184:187], v[202:205], v[54:57]
	v_mfma_f32_16x16x32_bf16 v[50:53], v[192:195], v[202:205], v[50:53]
	v_mfma_f32_16x16x32_bf16 v[38:41], v[184:187], v[210:213], v[38:41]
	v_mfma_f32_16x16x32_bf16 v[34:37], v[192:195], v[210:213], v[34:37]
	v_mfma_f32_16x16x32_bf16 v[22:25], v[184:187], v[218:221], v[22:25]
	v_mfma_f32_16x16x32_bf16 v[18:21], v[192:195], v[218:221], v[18:21]
	v_mfma_f32_16x16x32_bf16 v[6:9], v[184:187], v[226:229], v[6:9]
	v_mfma_f32_16x16x32_bf16 v[2:5], v[192:195], v[226:229], v[2:5]
	v_mfma_f32_16x16x32_bf16 v[54:57], v[188:191], v[206:209], v[54:57]
	v_mfma_f32_16x16x32_bf16 v[50:53], v[198:201], v[206:209], v[50:53]
	v_mfma_f32_16x16x32_bf16 v[38:41], v[188:191], v[214:217], v[38:41]
	v_mfma_f32_16x16x32_bf16 v[34:37], v[198:201], v[214:217], v[34:37]
	v_mfma_f32_16x16x32_bf16 v[22:25], v[188:191], v[222:225], v[22:25]
	v_mfma_f32_16x16x32_bf16 v[18:21], v[198:201], v[222:225], v[18:21]
	v_mfma_f32_16x16x32_bf16 v[6:9], v[188:191], v[230:233], v[6:9]
	v_mfma_f32_16x16x32_bf16 v[2:5], v[198:201], v[230:233], v[2:5]
	s_barrier
	s_setprio 0
	s_add_i32 s29, s29, 2
	s_add_u32 s8, s8, 0x100
	s_addc_u32 s9, s9, 0
	s_add_u32 s21, s21, 0x100
	s_addc_u32 s28, s28, 0
	s_cmp_gt_u32 s29, 61
	s_cbranch_scc0 .LBB0_126
	v_readlane_b32 s8, v249, 56
	v_readlane_b32 s9, v249, 57
	s_and_b64 vcc, exec, s[8:9]
	s_cbranch_vccz .LBB0_129
	s_barrier

.LBB0_678:
	ds_read_b128 v[148:151], v159
	ds_read_b128 v[152:155], v159 offset:1024
	ds_read_b128 v[164:167], v159 offset:2048
	ds_read_b128 v[168:171], v159 offset:3072
	ds_read_b128 v[172:175], v160
	ds_read_b128 v[176:179], v160 offset:1024
	ds_read_b128 v[180:183], v160 offset:2048
	ds_read_b128 v[184:187], v160 offset:3072
	s_add_u32 s60, s58, 0xfff00080
	s_addc_u32 s61, s59, -1
	s_cmp_eq_u32 s78, 60
	s_cselect_b32 s63, s7, s61
	s_cselect_b32 s62, s47, s60
	s_cselect_b32 s61, s45, s77
	s_cselect_b32 s60, s57, s76
	s_add_i32 m0, s64, 0xc000
	ds_read_b128 v[188:191], v161
	ds_read_b128 v[192:195], v161 offset:1024
	ds_read_b128 v[198:201], v161 offset:2048
	ds_read_b128 v[202:205], v161 offset:3072
	ds_read_b128 v[206:209], v161 offset:4096
	ds_read_b128 v[210:213], v161 offset:5120
	ds_read_b128 v[214:217], v161 offset:6144
	ds_read_b128 v[218:221], v161 offset:7168
	global_load_lds_dwordx4 v140, s[58:59]
	s_add_i32 m0, s64, 0xe000
	s_nop 0
	global_load_lds_dwordx4 v142, s[58:59]
	s_waitcnt vmcnt(8)
	s_waitcnt lgkmcnt(0)
	s_setprio 1
	s_barrier
	v_mfma_f32_16x16x32_bf16 v[126:129], v[148:151], v[188:191], v[126:129]
	v_mfma_f32_16x16x32_bf16 v[122:125], v[164:167], v[188:191], v[122:125]
	v_mfma_f32_16x16x32_bf16 v[110:113], v[148:151], v[198:201], v[110:113]
	v_mfma_f32_16x16x32_bf16 v[106:109], v[164:167], v[198:201], v[106:109]
	v_mfma_f32_16x16x32_bf16 v[94:97], v[148:151], v[206:209], v[94:97]
	v_mfma_f32_16x16x32_bf16 v[90:93], v[164:167], v[206:209], v[90:93]
	v_mfma_f32_16x16x32_bf16 v[78:81], v[148:151], v[214:217], v[78:81]
	v_mfma_f32_16x16x32_bf16 v[74:77], v[164:167], v[214:217], v[74:77]
	v_mfma_f32_16x16x32_bf16 v[126:129], v[152:155], v[192:195], v[126:129]
	v_mfma_f32_16x16x32_bf16 v[122:125], v[168:171], v[192:195], v[122:125]
	v_mfma_f32_16x16x32_bf16 v[110:113], v[152:155], v[202:205], v[110:113]
	v_mfma_f32_16x16x32_bf16 v[106:109], v[168:171], v[202:205], v[106:109]
	v_mfma_f32_16x16x32_bf16 v[94:97], v[152:155], v[210:213], v[94:97]
	v_mfma_f32_16x16x32_bf16 v[90:93], v[168:171], v[210:213], v[90:93]
	v_mfma_f32_16x16x32_bf16 v[78:81], v[152:155], v[218:221], v[78:81]
	v_mfma_f32_16x16x32_bf16 v[74:77], v[168:171], v[218:221], v[74:77]
	v_mfma_f32_16x16x32_bf16 v[118:121], v[172:175], v[188:191], v[118:121]
	v_mfma_f32_16x16x32_bf16 v[114:117], v[180:183], v[188:191], v[114:117]
	v_mfma_f32_16x16x32_bf16 v[102:105], v[172:175], v[198:201], v[102:105]
	v_mfma_f32_16x16x32_bf16 v[98:101], v[180:183], v[198:201], v[98:101]
	v_mfma_f32_16x16x32_bf16 v[86:89], v[172:175], v[206:209], v[86:89]
	v_mfma_f32_16x16x32_bf16 v[82:85], v[180:183], v[206:209], v[82:85]
	v_mfma_f32_16x16x32_bf16 v[70:73], v[172:175], v[214:217], v[70:73]
	v_mfma_f32_16x16x32_bf16 v[66:69], v[180:183], v[214:217], v[66:69]
	v_mfma_f32_16x16x32_bf16 v[118:121], v[176:179], v[192:195], v[118:121]
	v_mfma_f32_16x16x32_bf16 v[114:117], v[184:187], v[192:195], v[114:117]
	v_mfma_f32_16x16x32_bf16 v[102:105], v[176:179], v[202:205], v[102:105]
	v_mfma_f32_16x16x32_bf16 v[98:101], v[184:187], v[202:205], v[98:101]
	v_mfma_f32_16x16x32_bf16 v[86:89], v[176:179], v[210:213], v[86:89]
	v_mfma_f32_16x16x32_bf16 v[82:85], v[184:187], v[210:213], v[82:85]
	v_mfma_f32_16x16x32_bf16 v[70:73], v[176:179], v[218:221], v[70:73]
	v_mfma_f32_16x16x32_bf16 v[66:69], v[184:187], v[218:221], v[66:69]
	s_barrier
	s_setprio 0
	s_add_u32 s80, s60, 0x100000
	s_addc_u32 s81, s61, 0
	s_add_i32 m0, s33, 0x10000
	ds_read_b128 v[188:191], v161 offset:16384
	global_load_lds_dwordx4 v132, s[60:61]
	s_add_i32 m0, s33, 0x12000
	ds_read_b128 v[192:195], v161 offset:17408
	global_load_lds_dwordx4 v136, s[60:61]
	s_add_i32 m0, s33, 0x14000
	ds_read_b128 v[198:201], v161 offset:18432
	global_load_lds_dwordx4 v132, s[80:81]
	s_add_i32 m0, s33, 0x16000
	ds_read_b128 v[202:205], v161 offset:19456
	global_load_lds_dwordx4 v136, s[80:81]
	s_add_i32 m0, s33, 0x0
	ds_read_b128 v[206:209], v161 offset:20480
	global_load_lds_dwordx4 v130, s[62:63]
	s_add_i32 m0, s33, 0x2000
	ds_read_b128 v[210:213], v161 offset:21504
	global_load_lds_dwordx4 v134, s[62:63]
	ds_read_b128 v[214:217], v161 offset:22528
	ds_read_b128 v[218:221], v161 offset:23552
	s_waitcnt vmcnt(8)
	s_waitcnt lgkmcnt(0)
	s_setprio 1
	s_barrier
	v_mfma_f32_16x16x32_bf16 v[62:65], v[148:151], v[188:191], v[62:65]
	v_mfma_f32_16x16x32_bf16 v[58:61], v[164:167], v[188:191], v[58:61]
	v_mfma_f32_16x16x32_bf16 v[46:49], v[148:151], v[198:201], v[46:49]
	v_mfma_f32_16x16x32_bf16 v[42:45], v[164:167], v[198:201], v[42:45]
	v_mfma_f32_16x16x32_bf16 v[30:33], v[148:151], v[206:209], v[30:33]
	v_mfma_f32_16x16x32_bf16 v[26:29], v[164:167], v[206:209], v[26:29]
	v_mfma_f32_16x16x32_bf16 v[14:17], v[148:151], v[214:217], v[14:17]
	v_mfma_f32_16x16x32_bf16 v[10:13], v[164:167], v[214:217], v[10:13]
	v_mfma_f32_16x16x32_bf16 v[62:65], v[152:155], v[192:195], v[62:65]
	v_mfma_f32_16x16x32_bf16 v[58:61], v[168:171], v[192:195], v[58:61]
	v_mfma_f32_16x16x32_bf16 v[46:49], v[152:155], v[202:205], v[46:49]
	v_mfma_f32_16x16x32_bf16 v[42:45], v[168:171], v[202:205], v[42:45]
	v_mfma_f32_16x16x32_bf16 v[30:33], v[152:155], v[210:213], v[30:33]
	v_mfma_f32_16x16x32_bf16 v[26:29], v[168:171], v[210:213], v[26:29]
	v_mfma_f32_16x16x32_bf16 v[14:17], v[152:155], v[218:221], v[14:17]
	v_mfma_f32_16x16x32_bf16 v[10:13], v[168:171], v[218:221], v[10:13]
	v_mfma_f32_16x16x32_bf16 v[54:57], v[172:175], v[188:191], v[54:57]
	v_mfma_f32_16x16x32_bf16 v[50:53], v[180:183], v[188:191], v[50:53]
	v_mfma_f32_16x16x32_bf16 v[38:41], v[172:175], v[198:201], v[38:41]
	v_mfma_f32_16x16x32_bf16 v[34:37], v[180:183], v[198:201], v[34:37]
	v_mfma_f32_16x16x32_bf16 v[22:25], v[172:175], v[206:209], v[22:25]
	v_mfma_f32_16x16x32_bf16 v[18:21], v[180:183], v[206:209], v[18:21]
	v_mfma_f32_16x16x32_bf16 v[6:9], v[172:175], v[214:217], v[6:9]
	v_mfma_f32_16x16x32_bf16 v[2:5], v[180:183], v[214:217], v[2:5]
	v_mfma_f32_16x16x32_bf16 v[54:57], v[176:179], v[192:195], v[54:57]
	v_mfma_f32_16x16x32_bf16 v[50:53], v[184:187], v[192:195], v[50:53]
	v_mfma_f32_16x16x32_bf16 v[38:41], v[176:179], v[202:205], v[38:41]
	v_mfma_f32_16x16x32_bf16 v[34:37], v[184:187], v[202:205], v[34:37]
	v_mfma_f32_16x16x32_bf16 v[22:25], v[176:179], v[210:213], v[22:25]
	v_mfma_f32_16x16x32_bf16 v[18:21], v[184:187], v[210:213], v[18:21]
	v_mfma_f32_16x16x32_bf16 v[6:9], v[176:179], v[218:221], v[6:9]
	v_mfma_f32_16x16x32_bf16 v[2:5], v[184:187], v[218:221], v[2:5]
	s_barrier
	s_setprio 0
	s_add_i32 s79, 0, 0x18000
	v_add_u32_e32 v138, s79, v157
	s_add_i32 s80, 0, 0x1c000
	ds_read_b128 v[148:151], v138
	ds_read_b128 v[152:155], v138 offset:1024
	ds_read_b128 v[164:167], v138 offset:2048
	ds_read_b128 v[168:171], v138 offset:3072
	v_add_u32_e32 v138, s80, v157
	ds_read_b128 v[172:175], v138
	ds_read_b128 v[176:179], v138 offset:1024
	ds_read_b128 v[180:183], v138 offset:2048
	ds_read_b128 v[184:187], v138 offset:3072
	s_add_u32 s62, s62, 0x100000
	s_addc_u32 s63, s63, 0
	s_mov_b32 m0, s66
	ds_read_b128 v[188:191], v161 offset:32768
	ds_read_b128 v[192:195], v161 offset:33792
	ds_read_b128 v[198:201], v161 offset:34816
	ds_read_b128 v[202:205], v161 offset:35840
	ds_read_b128 v[206:209], v161 offset:36864
	ds_read_b128 v[210:213], v161 offset:37888
	ds_read_b128 v[214:217], v161 offset:38912
	ds_read_b128 v[218:221], v161 offset:39936
	global_load_lds_dwordx4 v130, s[62:63]
	s_mov_b32 m0, s67
	s_nop 0
	global_load_lds_dwordx4 v134, s[62:63]
	s_waitcnt vmcnt(8)
	s_waitcnt lgkmcnt(0)
	s_setprio 1
	s_barrier
	v_mfma_f32_16x16x32_bf16 v[126:129], v[148:151], v[188:191], v[126:129]
	v_mfma_f32_16x16x32_bf16 v[122:125], v[164:167], v[188:191], v[122:125]
	v_mfma_f32_16x16x32_bf16 v[110:113], v[148:151], v[198:201], v[110:113]
	v_mfma_f32_16x16x32_bf16 v[106:109], v[164:167], v[198:201], v[106:109]
	v_mfma_f32_16x16x32_bf16 v[94:97], v[148:151], v[206:209], v[94:97]
	v_mfma_f32_16x16x32_bf16 v[90:93], v[164:167], v[206:209], v[90:93]
	v_mfma_f32_16x16x32_bf16 v[78:81], v[148:151], v[214:217], v[78:81]
	v_mfma_f32_16x16x32_bf16 v[74:77], v[164:167], v[214:217], v[74:77]
	v_mfma_f32_16x16x32_bf16 v[126:129], v[152:155], v[192:195], v[126:129]
	v_mfma_f32_16x16x32_bf16 v[122:125], v[168:171], v[192:195], v[122:125]
	v_mfma_f32_16x16x32_bf16 v[110:113], v[152:155], v[202:205], v[110:113]
	v_mfma_f32_16x16x32_bf16 v[106:109], v[168:171], v[202:205], v[106:109]
	v_mfma_f32_16x16x32_bf16 v[94:97], v[152:155], v[210:213], v[94:97]
	v_mfma_f32_16x16x32_bf16 v[90:93], v[168:171], v[210:213], v[90:93]
	v_mfma_f32_16x16x32_bf16 v[78:81], v[152:155], v[218:221], v[78:81]
	v_mfma_f32_16x16x32_bf16 v[74:77], v[168:171], v[218:221], v[74:77]
	v_mfma_f32_16x16x32_bf16 v[118:121], v[172:175], v[188:191], v[118:121]
	v_mfma_f32_16x16x32_bf16 v[114:117], v[180:183], v[188:191], v[114:117]
	v_mfma_f32_16x16x32_bf16 v[102:105], v[172:175], v[198:201], v[102:105]
	v_mfma_f32_16x16x32_bf16 v[98:101], v[180:183], v[198:201], v[98:101]
	v_mfma_f32_16x16x32_bf16 v[86:89], v[172:175], v[206:209], v[86:89]
	v_mfma_f32_16x16x32_bf16 v[82:85], v[180:183], v[206:209], v[82:85]
	v_mfma_f32_16x16x32_bf16 v[70:73], v[172:175], v[214:217], v[70:73]
	v_mfma_f32_16x16x32_bf16 v[66:69], v[180:183], v[214:217], v[66:69]
	v_mfma_f32_16x16x32_bf16 v[118:121], v[176:179], v[192:195], v[118:121]
	v_mfma_f32_16x16x32_bf16 v[114:117], v[184:187], v[192:195], v[114:117]
	v_mfma_f32_16x16x32_bf16 v[102:105], v[176:179], v[202:205], v[102:105]
	v_mfma_f32_16x16x32_bf16 v[98:101], v[184:187], v[202:205], v[98:101]
	v_mfma_f32_16x16x32_bf16 v[86:89], v[176:179], v[210:213], v[86:89]
	v_mfma_f32_16x16x32_bf16 v[82:85], v[184:187], v[210:213], v[82:85]
	v_mfma_f32_16x16x32_bf16 v[70:73], v[176:179], v[218:221], v[70:73]
	v_mfma_f32_16x16x32_bf16 v[66:69], v[184:187], v[218:221], v[66:69]
	s_barrier
	s_setprio 0
	s_add_u32 s60, s60, 0x80
	s_addc_u32 s61, s61, 0
	s_add_u32 s80, s60, 0x100000
	s_addc_u32 s81, s61, 0
	s_add_u32 s62, s62, 0xfff00080
	s_addc_u32 s63, s63, -1
	s_add_i32 m0, s33, 0x18000
	ds_read_b128 v[188:191], v161 offset:49152
	global_load_lds_dwordx4 v132, s[60:61]
	s_add_i32 m0, s33, 0x1a000
	ds_read_b128 v[192:195], v161 offset:50176
	global_load_lds_dwordx4 v136, s[60:61]
	s_add_i32 m0, s33, 0x1c000
	ds_read_b128 v[198:201], v161 offset:51200
	global_load_lds_dwordx4 v132, s[80:81]
	s_add_i32 m0, s33, 0x1e000
	ds_read_b128 v[202:205], v161 offset:52224
	global_load_lds_dwordx4 v136, s[80:81]
	s_add_i32 m0, s33, 0x8000
	ds_read_b128 v[206:209], v161 offset:53248
	global_load_lds_dwordx4 v130, s[62:63]
	s_add_i32 m0, s33, 0xa000
	ds_read_b128 v[210:213], v161 offset:54272
	global_load_lds_dwordx4 v134, s[62:63]
	ds_read_b128 v[214:217], v161 offset:55296
	ds_read_b128 v[218:221], v161 offset:56320
	s_waitcnt vmcnt(8)
	s_waitcnt lgkmcnt(0)
	s_setprio 1
	s_barrier
	v_mfma_f32_16x16x32_bf16 v[62:65], v[148:151], v[188:191], v[62:65]
	v_mfma_f32_16x16x32_bf16 v[58:61], v[164:167], v[188:191], v[58:61]
	v_mfma_f32_16x16x32_bf16 v[46:49], v[148:151], v[198:201], v[46:49]
	v_mfma_f32_16x16x32_bf16 v[42:45], v[164:167], v[198:201], v[42:45]
	v_mfma_f32_16x16x32_bf16 v[30:33], v[148:151], v[206:209], v[30:33]
	v_mfma_f32_16x16x32_bf16 v[26:29], v[164:167], v[206:209], v[26:29]
	v_mfma_f32_16x16x32_bf16 v[14:17], v[148:151], v[214:217], v[14:17]
	v_mfma_f32_16x16x32_bf16 v[10:13], v[164:167], v[214:217], v[10:13]
	v_mfma_f32_16x16x32_bf16 v[62:65], v[152:155], v[192:195], v[62:65]
	v_mfma_f32_16x16x32_bf16 v[58:61], v[168:171], v[192:195], v[58:61]
	v_mfma_f32_16x16x32_bf16 v[46:49], v[152:155], v[202:205], v[46:49]
	v_mfma_f32_16x16x32_bf16 v[42:45], v[168:171], v[202:205], v[42:45]
	v_mfma_f32_16x16x32_bf16 v[30:33], v[152:155], v[210:213], v[30:33]
	v_mfma_f32_16x16x32_bf16 v[26:29], v[168:171], v[210:213], v[26:29]
	v_mfma_f32_16x16x32_bf16 v[14:17], v[152:155], v[218:221], v[14:17]
	v_mfma_f32_16x16x32_bf16 v[10:13], v[168:171], v[218:221], v[10:13]
	v_mfma_f32_16x16x32_bf16 v[54:57], v[172:175], v[188:191], v[54:57]
	v_mfma_f32_16x16x32_bf16 v[50:53], v[180:183], v[188:191], v[50:53]
	v_mfma_f32_16x16x32_bf16 v[38:41], v[172:175], v[198:201], v[38:41]
	v_mfma_f32_16x16x32_bf16 v[34:37], v[180:183], v[198:201], v[34:37]
	v_mfma_f32_16x16x32_bf16 v[22:25], v[172:175], v[206:209], v[22:25]
	v_mfma_f32_16x16x32_bf16 v[18:21], v[180:183], v[206:209], v[18:21]
	v_mfma_f32_16x16x32_bf16 v[6:9], v[172:175], v[214:217], v[6:9]
	v_mfma_f32_16x16x32_bf16 v[2:5], v[180:183], v[214:217], v[2:5]
	v_mfma_f32_16x16x32_bf16 v[54:57], v[176:179], v[192:195], v[54:57]
	v_mfma_f32_16x16x32_bf16 v[50:53], v[184:187], v[192:195], v[50:53]
	v_mfma_f32_16x16x32_bf16 v[38:41], v[176:179], v[202:205], v[38:41]
	v_mfma_f32_16x16x32_bf16 v[34:37], v[184:187], v[202:205], v[34:37]
	v_mfma_f32_16x16x32_bf16 v[22:25], v[176:179], v[210:213], v[22:25]
	v_mfma_f32_16x16x32_bf16 v[18:21], v[184:187], v[210:213], v[18:21]
	v_mfma_f32_16x16x32_bf16 v[6:9], v[176:179], v[218:221], v[6:9]
	v_mfma_f32_16x16x32_bf16 v[2:5], v[184:187], v[218:221], v[2:5]
	s_barrier
	s_setprio 0
	s_add_i32 s78, s78, 2
	s_add_u32 s58, s58, 0x100
	s_addc_u32 s59, s59, 0
	s_add_u32 s76, s76, 0x100
	s_addc_u32 s77, s77, 0
	s_cmp_gt_u32 s78, 61
	s_cbranch_scc0 .LBB0_678
	s_and_b64 vcc, exec, s[18:19]
	s_cbranch_vccz .LBB0_681
	s_barrier

.LBB0_807:
	ds_read_b128 v[154:157], v150
	ds_read_b128 v[158:161], v150 offset:1024
	ds_read_b128 v[162:165], v150 offset:2048
	ds_read_b128 v[166:169], v150 offset:3072
	ds_read_b128 v[170:173], v151
	ds_read_b128 v[174:177], v151 offset:1024
	ds_read_b128 v[178:181], v151 offset:2048
	ds_read_b128 v[182:185], v151 offset:3072
	s_add_u32 s44, s42, 0xfff00080
	s_addc_u32 s45, s43, -1
	s_cmp_eq_u32 s68, 60
	s_cselect_b32 s47, s35, s45
	s_cselect_b32 s46, s64, s44
	s_cselect_b32 s45, s31, s67
	s_cselect_b32 s44, s65, s66
	s_add_i32 m0, s41, 0xc000
	ds_read_b128 v[186:189], v152
	ds_read_b128 v[190:193], v152 offset:1024
	ds_read_b128 v[198:201], v152 offset:2048
	ds_read_b128 v[202:205], v152 offset:3072
	ds_read_b128 v[206:209], v152 offset:4096
	ds_read_b128 v[210:213], v152 offset:5120
	ds_read_b128 v[214:217], v152 offset:6144
	ds_read_b128 v[218:221], v152 offset:7168
	global_load_lds_dwordx4 v138, s[42:43]
	s_add_i32 m0, s41, 0xe000
	s_nop 0
	global_load_lds_dwordx4 v140, s[42:43]
	s_waitcnt vmcnt(8)
	s_waitcnt lgkmcnt(0)
	s_setprio 1
	s_barrier
	v_mfma_f32_16x16x32_bf16 v[126:129], v[154:157], v[186:189], v[126:129]
	v_mfma_f32_16x16x32_bf16 v[122:125], v[162:165], v[186:189], v[122:125]
	v_mfma_f32_16x16x32_bf16 v[110:113], v[154:157], v[198:201], v[110:113]
	v_mfma_f32_16x16x32_bf16 v[106:109], v[162:165], v[198:201], v[106:109]
	v_mfma_f32_16x16x32_bf16 v[94:97], v[154:157], v[206:209], v[94:97]
	v_mfma_f32_16x16x32_bf16 v[90:93], v[162:165], v[206:209], v[90:93]
	v_mfma_f32_16x16x32_bf16 v[78:81], v[154:157], v[214:217], v[78:81]
	v_mfma_f32_16x16x32_bf16 v[74:77], v[162:165], v[214:217], v[74:77]
	v_mfma_f32_16x16x32_bf16 v[126:129], v[158:161], v[190:193], v[126:129]
	v_mfma_f32_16x16x32_bf16 v[122:125], v[166:169], v[190:193], v[122:125]
	v_mfma_f32_16x16x32_bf16 v[110:113], v[158:161], v[202:205], v[110:113]
	v_mfma_f32_16x16x32_bf16 v[106:109], v[166:169], v[202:205], v[106:109]
	v_mfma_f32_16x16x32_bf16 v[94:97], v[158:161], v[210:213], v[94:97]
	v_mfma_f32_16x16x32_bf16 v[90:93], v[166:169], v[210:213], v[90:93]
	v_mfma_f32_16x16x32_bf16 v[78:81], v[158:161], v[218:221], v[78:81]
	v_mfma_f32_16x16x32_bf16 v[74:77], v[166:169], v[218:221], v[74:77]
	v_mfma_f32_16x16x32_bf16 v[118:121], v[170:173], v[186:189], v[118:121]
	v_mfma_f32_16x16x32_bf16 v[114:117], v[178:181], v[186:189], v[114:117]
	v_mfma_f32_16x16x32_bf16 v[102:105], v[170:173], v[198:201], v[102:105]
	v_mfma_f32_16x16x32_bf16 v[98:101], v[178:181], v[198:201], v[98:101]
	v_mfma_f32_16x16x32_bf16 v[86:89], v[170:173], v[206:209], v[86:89]
	v_mfma_f32_16x16x32_bf16 v[82:85], v[178:181], v[206:209], v[82:85]
	v_mfma_f32_16x16x32_bf16 v[70:73], v[170:173], v[214:217], v[70:73]
	v_mfma_f32_16x16x32_bf16 v[66:69], v[178:181], v[214:217], v[66:69]
	v_mfma_f32_16x16x32_bf16 v[118:121], v[174:177], v[190:193], v[118:121]
	v_mfma_f32_16x16x32_bf16 v[114:117], v[182:185], v[190:193], v[114:117]
	v_mfma_f32_16x16x32_bf16 v[102:105], v[174:177], v[202:205], v[102:105]
	v_mfma_f32_16x16x32_bf16 v[98:101], v[182:185], v[202:205], v[98:101]
	v_mfma_f32_16x16x32_bf16 v[86:89], v[174:177], v[210:213], v[86:89]
	v_mfma_f32_16x16x32_bf16 v[82:85], v[182:185], v[210:213], v[82:85]
	v_mfma_f32_16x16x32_bf16 v[70:73], v[174:177], v[218:221], v[70:73]
	v_mfma_f32_16x16x32_bf16 v[66:69], v[182:185], v[218:221], v[66:69]
	s_barrier
	s_setprio 0
	s_add_u32 s70, s44, 0x100000
	s_addc_u32 s71, s45, 0
	s_add_i32 m0, s33, 0x10000
	ds_read_b128 v[186:189], v152 offset:16384
	global_load_lds_dwordx4 v132, s[44:45]
	s_add_i32 m0, s33, 0x12000
	ds_read_b128 v[190:193], v152 offset:17408
	global_load_lds_dwordx4 v136, s[44:45]
	s_add_i32 m0, s33, 0x14000
	ds_read_b128 v[198:201], v152 offset:18432
	global_load_lds_dwordx4 v132, s[70:71]
	s_add_i32 m0, s33, 0x16000
	ds_read_b128 v[202:205], v152 offset:19456
	global_load_lds_dwordx4 v136, s[70:71]
	s_add_i32 m0, s33, 0x0
	ds_read_b128 v[206:209], v152 offset:20480
	global_load_lds_dwordx4 v130, s[46:47]
	s_add_i32 m0, s33, 0x2000
	ds_read_b128 v[210:213], v152 offset:21504
	global_load_lds_dwordx4 v134, s[46:47]
	ds_read_b128 v[214:217], v152 offset:22528
	ds_read_b128 v[218:221], v152 offset:23552
	s_waitcnt vmcnt(8)
	s_waitcnt lgkmcnt(0)
	s_setprio 1
	s_barrier
	v_mfma_f32_16x16x32_bf16 v[62:65], v[154:157], v[186:189], v[62:65]
	v_mfma_f32_16x16x32_bf16 v[58:61], v[162:165], v[186:189], v[58:61]
	v_mfma_f32_16x16x32_bf16 v[46:49], v[154:157], v[198:201], v[46:49]
	v_mfma_f32_16x16x32_bf16 v[42:45], v[162:165], v[198:201], v[42:45]
	v_mfma_f32_16x16x32_bf16 v[30:33], v[154:157], v[206:209], v[30:33]
	v_mfma_f32_16x16x32_bf16 v[26:29], v[162:165], v[206:209], v[26:29]
	v_mfma_f32_16x16x32_bf16 v[14:17], v[154:157], v[214:217], v[14:17]
	v_mfma_f32_16x16x32_bf16 v[10:13], v[162:165], v[214:217], v[10:13]
	v_mfma_f32_16x16x32_bf16 v[62:65], v[158:161], v[190:193], v[62:65]
	v_mfma_f32_16x16x32_bf16 v[58:61], v[166:169], v[190:193], v[58:61]
	v_mfma_f32_16x16x32_bf16 v[46:49], v[158:161], v[202:205], v[46:49]
	v_mfma_f32_16x16x32_bf16 v[42:45], v[166:169], v[202:205], v[42:45]
	v_mfma_f32_16x16x32_bf16 v[30:33], v[158:161], v[210:213], v[30:33]
	v_mfma_f32_16x16x32_bf16 v[26:29], v[166:169], v[210:213], v[26:29]
	v_mfma_f32_16x16x32_bf16 v[14:17], v[158:161], v[218:221], v[14:17]
	v_mfma_f32_16x16x32_bf16 v[10:13], v[166:169], v[218:221], v[10:13]
	v_mfma_f32_16x16x32_bf16 v[54:57], v[170:173], v[186:189], v[54:57]
	v_mfma_f32_16x16x32_bf16 v[50:53], v[178:181], v[186:189], v[50:53]
	v_mfma_f32_16x16x32_bf16 v[38:41], v[170:173], v[198:201], v[38:41]
	v_mfma_f32_16x16x32_bf16 v[34:37], v[178:181], v[198:201], v[34:37]
	v_mfma_f32_16x16x32_bf16 v[22:25], v[170:173], v[206:209], v[22:25]
	v_mfma_f32_16x16x32_bf16 v[18:21], v[178:181], v[206:209], v[18:21]
	v_mfma_f32_16x16x32_bf16 v[6:9], v[170:173], v[214:217], v[6:9]
	v_mfma_f32_16x16x32_bf16 v[2:5], v[178:181], v[214:217], v[2:5]
	v_mfma_f32_16x16x32_bf16 v[54:57], v[174:177], v[190:193], v[54:57]
	v_mfma_f32_16x16x32_bf16 v[50:53], v[182:185], v[190:193], v[50:53]
	v_mfma_f32_16x16x32_bf16 v[38:41], v[174:177], v[202:205], v[38:41]
	v_mfma_f32_16x16x32_bf16 v[34:37], v[182:185], v[202:205], v[34:37]
	v_mfma_f32_16x16x32_bf16 v[22:25], v[174:177], v[210:213], v[22:25]
	v_mfma_f32_16x16x32_bf16 v[18:21], v[182:185], v[210:213], v[18:21]
	v_mfma_f32_16x16x32_bf16 v[6:9], v[174:177], v[218:221], v[6:9]
	v_mfma_f32_16x16x32_bf16 v[2:5], v[182:185], v[218:221], v[2:5]
	s_barrier
	s_setprio 0
	s_add_i32 s69, 0, 0x18000
	v_add_u32_e32 v153, s69, v148
	s_add_i32 s70, 0, 0x1c000
	ds_read_b128 v[154:157], v153
	ds_read_b128 v[158:161], v153 offset:1024
	ds_read_b128 v[162:165], v153 offset:2048
	ds_read_b128 v[166:169], v153 offset:3072
	v_add_u32_e32 v153, s70, v148
	ds_read_b128 v[170:173], v153
	ds_read_b128 v[174:177], v153 offset:1024
	ds_read_b128 v[178:181], v153 offset:2048
	ds_read_b128 v[182:185], v153 offset:3072
	s_add_u32 s46, s46, 0x100000
	s_addc_u32 s47, s47, 0
	s_mov_b32 m0, s51
	ds_read_b128 v[186:189], v152 offset:32768
	ds_read_b128 v[190:193], v152 offset:33792
	ds_read_b128 v[198:201], v152 offset:34816
	ds_read_b128 v[202:205], v152 offset:35840
	ds_read_b128 v[206:209], v152 offset:36864
	ds_read_b128 v[210:213], v152 offset:37888
	ds_read_b128 v[214:217], v152 offset:38912
	ds_read_b128 v[218:221], v152 offset:39936
	global_load_lds_dwordx4 v130, s[46:47]
	s_mov_b32 m0, s52
	s_nop 0
	global_load_lds_dwordx4 v134, s[46:47]
	s_waitcnt vmcnt(8)
	s_waitcnt lgkmcnt(0)
	s_setprio 1
	s_barrier
	v_mfma_f32_16x16x32_bf16 v[126:129], v[154:157], v[186:189], v[126:129]
	v_mfma_f32_16x16x32_bf16 v[122:125], v[162:165], v[186:189], v[122:125]
	v_mfma_f32_16x16x32_bf16 v[110:113], v[154:157], v[198:201], v[110:113]
	v_mfma_f32_16x16x32_bf16 v[106:109], v[162:165], v[198:201], v[106:109]
	v_mfma_f32_16x16x32_bf16 v[94:97], v[154:157], v[206:209], v[94:97]
	v_mfma_f32_16x16x32_bf16 v[90:93], v[162:165], v[206:209], v[90:93]
	v_mfma_f32_16x16x32_bf16 v[78:81], v[154:157], v[214:217], v[78:81]
	v_mfma_f32_16x16x32_bf16 v[74:77], v[162:165], v[214:217], v[74:77]
	v_mfma_f32_16x16x32_bf16 v[126:129], v[158:161], v[190:193], v[126:129]
	v_mfma_f32_16x16x32_bf16 v[122:125], v[166:169], v[190:193], v[122:125]
	v_mfma_f32_16x16x32_bf16 v[110:113], v[158:161], v[202:205], v[110:113]
	v_mfma_f32_16x16x32_bf16 v[106:109], v[166:169], v[202:205], v[106:109]
	v_mfma_f32_16x16x32_bf16 v[94:97], v[158:161], v[210:213], v[94:97]
	v_mfma_f32_16x16x32_bf16 v[90:93], v[166:169], v[210:213], v[90:93]
	v_mfma_f32_16x16x32_bf16 v[78:81], v[158:161], v[218:221], v[78:81]
	v_mfma_f32_16x16x32_bf16 v[74:77], v[166:169], v[218:221], v[74:77]
	v_mfma_f32_16x16x32_bf16 v[118:121], v[170:173], v[186:189], v[118:121]
	v_mfma_f32_16x16x32_bf16 v[114:117], v[178:181], v[186:189], v[114:117]
	v_mfma_f32_16x16x32_bf16 v[102:105], v[170:173], v[198:201], v[102:105]
	v_mfma_f32_16x16x32_bf16 v[98:101], v[178:181], v[198:201], v[98:101]
	v_mfma_f32_16x16x32_bf16 v[86:89], v[170:173], v[206:209], v[86:89]
	v_mfma_f32_16x16x32_bf16 v[82:85], v[178:181], v[206:209], v[82:85]
	v_mfma_f32_16x16x32_bf16 v[70:73], v[170:173], v[214:217], v[70:73]
	v_mfma_f32_16x16x32_bf16 v[66:69], v[178:181], v[214:217], v[66:69]
	v_mfma_f32_16x16x32_bf16 v[118:121], v[174:177], v[190:193], v[118:121]
	v_mfma_f32_16x16x32_bf16 v[114:117], v[182:185], v[190:193], v[114:117]
	v_mfma_f32_16x16x32_bf16 v[102:105], v[174:177], v[202:205], v[102:105]
	v_mfma_f32_16x16x32_bf16 v[98:101], v[182:185], v[202:205], v[98:101]
	v_mfma_f32_16x16x32_bf16 v[86:89], v[174:177], v[210:213], v[86:89]
	v_mfma_f32_16x16x32_bf16 v[82:85], v[182:185], v[210:213], v[82:85]
	v_mfma_f32_16x16x32_bf16 v[70:73], v[174:177], v[218:221], v[70:73]
	v_mfma_f32_16x16x32_bf16 v[66:69], v[182:185], v[218:221], v[66:69]
	s_barrier
	s_setprio 0
	s_add_u32 s44, s44, 0x80
	s_addc_u32 s45, s45, 0
	s_add_u32 s70, s44, 0x100000
	s_addc_u32 s71, s45, 0
	s_add_u32 s46, s46, 0xfff00080
	s_addc_u32 s47, s47, -1
	s_add_i32 m0, s33, 0x18000
	ds_read_b128 v[186:189], v152 offset:49152
	global_load_lds_dwordx4 v132, s[44:45]
	s_add_i32 m0, s33, 0x1a000
	ds_read_b128 v[190:193], v152 offset:50176
	global_load_lds_dwordx4 v136, s[44:45]
	s_add_i32 m0, s33, 0x1c000
	ds_read_b128 v[198:201], v152 offset:51200
	global_load_lds_dwordx4 v132, s[70:71]
	s_add_i32 m0, s33, 0x1e000
	ds_read_b128 v[202:205], v152 offset:52224
	global_load_lds_dwordx4 v136, s[70:71]
	s_add_i32 m0, s33, 0x8000
	ds_read_b128 v[206:209], v152 offset:53248
	global_load_lds_dwordx4 v130, s[46:47]
	s_add_i32 m0, s33, 0xa000
	ds_read_b128 v[210:213], v152 offset:54272
	global_load_lds_dwordx4 v134, s[46:47]
	ds_read_b128 v[214:217], v152 offset:55296
	ds_read_b128 v[218:221], v152 offset:56320
	s_waitcnt vmcnt(8)
	s_waitcnt lgkmcnt(0)
	s_setprio 1
	s_barrier
	v_mfma_f32_16x16x32_bf16 v[62:65], v[154:157], v[186:189], v[62:65]
	v_mfma_f32_16x16x32_bf16 v[58:61], v[162:165], v[186:189], v[58:61]
	v_mfma_f32_16x16x32_bf16 v[46:49], v[154:157], v[198:201], v[46:49]
	v_mfma_f32_16x16x32_bf16 v[42:45], v[162:165], v[198:201], v[42:45]
	v_mfma_f32_16x16x32_bf16 v[30:33], v[154:157], v[206:209], v[30:33]
	v_mfma_f32_16x16x32_bf16 v[26:29], v[162:165], v[206:209], v[26:29]
	v_mfma_f32_16x16x32_bf16 v[14:17], v[154:157], v[214:217], v[14:17]
	v_mfma_f32_16x16x32_bf16 v[10:13], v[162:165], v[214:217], v[10:13]
	v_mfma_f32_16x16x32_bf16 v[62:65], v[158:161], v[190:193], v[62:65]
	v_mfma_f32_16x16x32_bf16 v[58:61], v[166:169], v[190:193], v[58:61]
	v_mfma_f32_16x16x32_bf16 v[46:49], v[158:161], v[202:205], v[46:49]
	v_mfma_f32_16x16x32_bf16 v[42:45], v[166:169], v[202:205], v[42:45]
	v_mfma_f32_16x16x32_bf16 v[30:33], v[158:161], v[210:213], v[30:33]
	v_mfma_f32_16x16x32_bf16 v[26:29], v[166:169], v[210:213], v[26:29]
	v_mfma_f32_16x16x32_bf16 v[14:17], v[158:161], v[218:221], v[14:17]
	v_mfma_f32_16x16x32_bf16 v[10:13], v[166:169], v[218:221], v[10:13]
	v_mfma_f32_16x16x32_bf16 v[54:57], v[170:173], v[186:189], v[54:57]
	v_mfma_f32_16x16x32_bf16 v[50:53], v[178:181], v[186:189], v[50:53]
	v_mfma_f32_16x16x32_bf16 v[38:41], v[170:173], v[198:201], v[38:41]
	v_mfma_f32_16x16x32_bf16 v[34:37], v[178:181], v[198:201], v[34:37]
	v_mfma_f32_16x16x32_bf16 v[22:25], v[170:173], v[206:209], v[22:25]
	v_mfma_f32_16x16x32_bf16 v[18:21], v[178:181], v[206:209], v[18:21]
	v_mfma_f32_16x16x32_bf16 v[6:9], v[170:173], v[214:217], v[6:9]
	v_mfma_f32_16x16x32_bf16 v[2:5], v[178:181], v[214:217], v[2:5]
	v_mfma_f32_16x16x32_bf16 v[54:57], v[174:177], v[190:193], v[54:57]
	v_mfma_f32_16x16x32_bf16 v[50:53], v[182:185], v[190:193], v[50:53]
	v_mfma_f32_16x16x32_bf16 v[38:41], v[174:177], v[202:205], v[38:41]
	v_mfma_f32_16x16x32_bf16 v[34:37], v[182:185], v[202:205], v[34:37]
	v_mfma_f32_16x16x32_bf16 v[22:25], v[174:177], v[210:213], v[22:25]
	v_mfma_f32_16x16x32_bf16 v[18:21], v[182:185], v[210:213], v[18:21]
	v_mfma_f32_16x16x32_bf16 v[6:9], v[174:177], v[218:221], v[6:9]
	v_mfma_f32_16x16x32_bf16 v[2:5], v[182:185], v[218:221], v[2:5]
	s_barrier
	s_setprio 0
	s_add_i32 s68, s68, 2
	s_add_u32 s42, s42, 0x100
	s_addc_u32 s43, s43, 0
	s_add_u32 s66, s66, 0x100
	s_addc_u32 s67, s67, 0
	s_cmp_gt_u32 s68, 61
	s_cbranch_scc0 .LBB0_807
	s_and_b64 vcc, exec, s[14:15]
	s_cbranch_vccz .LBB0_810
	s_barrier

.LBB0_897:
	ds_read_b128 v[146:149], v156
	ds_read_b128 v[150:153], v156 offset:1024
	ds_read_b128 v[160:163], v156 offset:2048
	ds_read_b128 v[164:167], v156 offset:3072
	ds_read_b128 v[168:171], v157
	ds_read_b128 v[172:175], v157 offset:1024
	ds_read_b128 v[176:179], v157 offset:2048
	ds_read_b128 v[180:183], v157 offset:3072
	s_add_u32 s44, s42, 0xffc00080
	s_addc_u32 s45, s43, -1
	s_cmpk_eq_i32 s67, 0xfc
	s_cselect_b32 s47, s35, s45
	s_cselect_b32 s46, s63, s44
	s_cselect_b32 s45, s31, s66
	s_cselect_b32 s44, s64, s65
	s_add_i32 m0, s41, 0xc000
	ds_read_b128 v[184:187], v158
	ds_read_b128 v[188:191], v158 offset:1024
	ds_read_b128 v[192:195], v158 offset:2048
	ds_read_b128 v[198:201], v158 offset:3072
	ds_read_b128 v[202:205], v158 offset:4096
	ds_read_b128 v[206:209], v158 offset:5120
	ds_read_b128 v[210:213], v158 offset:6144
	ds_read_b128 v[214:217], v158 offset:7168
	global_load_lds_dwordx4 v138, s[42:43]
	s_add_i32 m0, s41, 0xe000
	s_nop 0
	global_load_lds_dwordx4 v140, s[42:43]
	s_waitcnt vmcnt(8)
	s_waitcnt lgkmcnt(0)
	s_setprio 1
	s_barrier
	v_mfma_f32_16x16x32_bf16 v[126:129], v[146:149], v[184:187], v[126:129]
	v_mfma_f32_16x16x32_bf16 v[122:125], v[160:163], v[184:187], v[122:125]
	v_mfma_f32_16x16x32_bf16 v[110:113], v[146:149], v[192:195], v[110:113]
	v_mfma_f32_16x16x32_bf16 v[106:109], v[160:163], v[192:195], v[106:109]
	v_mfma_f32_16x16x32_bf16 v[94:97], v[146:149], v[202:205], v[94:97]
	v_mfma_f32_16x16x32_bf16 v[90:93], v[160:163], v[202:205], v[90:93]
	v_mfma_f32_16x16x32_bf16 v[78:81], v[146:149], v[210:213], v[78:81]
	v_mfma_f32_16x16x32_bf16 v[74:77], v[160:163], v[210:213], v[74:77]
	v_mfma_f32_16x16x32_bf16 v[126:129], v[150:153], v[188:191], v[126:129]
	v_mfma_f32_16x16x32_bf16 v[122:125], v[164:167], v[188:191], v[122:125]
	v_mfma_f32_16x16x32_bf16 v[110:113], v[150:153], v[198:201], v[110:113]
	v_mfma_f32_16x16x32_bf16 v[106:109], v[164:167], v[198:201], v[106:109]
	v_mfma_f32_16x16x32_bf16 v[94:97], v[150:153], v[206:209], v[94:97]
	v_mfma_f32_16x16x32_bf16 v[90:93], v[164:167], v[206:209], v[90:93]
	v_mfma_f32_16x16x32_bf16 v[78:81], v[150:153], v[214:217], v[78:81]
	v_mfma_f32_16x16x32_bf16 v[74:77], v[164:167], v[214:217], v[74:77]
	v_mfma_f32_16x16x32_bf16 v[118:121], v[168:171], v[184:187], v[118:121]
	v_mfma_f32_16x16x32_bf16 v[114:117], v[176:179], v[184:187], v[114:117]
	v_mfma_f32_16x16x32_bf16 v[102:105], v[168:171], v[192:195], v[102:105]
	v_mfma_f32_16x16x32_bf16 v[98:101], v[176:179], v[192:195], v[98:101]
	v_mfma_f32_16x16x32_bf16 v[86:89], v[168:171], v[202:205], v[86:89]
	v_mfma_f32_16x16x32_bf16 v[82:85], v[176:179], v[202:205], v[82:85]
	v_mfma_f32_16x16x32_bf16 v[70:73], v[168:171], v[210:213], v[70:73]
	v_mfma_f32_16x16x32_bf16 v[66:69], v[176:179], v[210:213], v[66:69]
	v_mfma_f32_16x16x32_bf16 v[118:121], v[172:175], v[188:191], v[118:121]
	v_mfma_f32_16x16x32_bf16 v[114:117], v[180:183], v[188:191], v[114:117]
	v_mfma_f32_16x16x32_bf16 v[102:105], v[172:175], v[198:201], v[102:105]
	v_mfma_f32_16x16x32_bf16 v[98:101], v[180:183], v[198:201], v[98:101]
	v_mfma_f32_16x16x32_bf16 v[86:89], v[172:175], v[206:209], v[86:89]
	v_mfma_f32_16x16x32_bf16 v[82:85], v[180:183], v[206:209], v[82:85]
	v_mfma_f32_16x16x32_bf16 v[70:73], v[172:175], v[214:217], v[70:73]
	v_mfma_f32_16x16x32_bf16 v[66:69], v[180:183], v[214:217], v[66:69]
	s_barrier
	s_setprio 0
	s_add_u32 s68, s44, 0x400000
	s_addc_u32 s69, s45, 0
	s_add_i32 m0, s48, 0x10000
	ds_read_b128 v[184:187], v158 offset:16384
	global_load_lds_dwordx4 v132, s[44:45]
	s_add_i32 m0, s48, 0x12000
	ds_read_b128 v[188:191], v158 offset:17408
	global_load_lds_dwordx4 v136, s[44:45]
	s_add_i32 m0, s48, 0x14000
	ds_read_b128 v[192:195], v158 offset:18432
	global_load_lds_dwordx4 v132, s[68:69]
	s_add_i32 m0, s48, 0x16000
	ds_read_b128 v[198:201], v158 offset:19456
	global_load_lds_dwordx4 v136, s[68:69]
	s_add_i32 m0, s48, 0x0
	ds_read_b128 v[202:205], v158 offset:20480
	global_load_lds_dwordx4 v130, s[46:47]
	s_add_i32 m0, s48, 0x2000
	ds_read_b128 v[206:209], v158 offset:21504
	global_load_lds_dwordx4 v134, s[46:47]
	ds_read_b128 v[210:213], v158 offset:22528
	ds_read_b128 v[214:217], v158 offset:23552
	s_waitcnt vmcnt(8)
	s_waitcnt lgkmcnt(0)
	s_setprio 1
	s_barrier
	v_mfma_f32_16x16x32_bf16 v[62:65], v[146:149], v[184:187], v[62:65]
	v_mfma_f32_16x16x32_bf16 v[58:61], v[160:163], v[184:187], v[58:61]
	v_mfma_f32_16x16x32_bf16 v[46:49], v[146:149], v[192:195], v[46:49]
	v_mfma_f32_16x16x32_bf16 v[42:45], v[160:163], v[192:195], v[42:45]
	v_mfma_f32_16x16x32_bf16 v[30:33], v[146:149], v[202:205], v[30:33]
	v_mfma_f32_16x16x32_bf16 v[26:29], v[160:163], v[202:205], v[26:29]
	v_mfma_f32_16x16x32_bf16 v[14:17], v[146:149], v[210:213], v[14:17]
	v_mfma_f32_16x16x32_bf16 v[10:13], v[160:163], v[210:213], v[10:13]
	v_mfma_f32_16x16x32_bf16 v[62:65], v[150:153], v[188:191], v[62:65]
	v_mfma_f32_16x16x32_bf16 v[58:61], v[164:167], v[188:191], v[58:61]
	v_mfma_f32_16x16x32_bf16 v[46:49], v[150:153], v[198:201], v[46:49]
	v_mfma_f32_16x16x32_bf16 v[42:45], v[164:167], v[198:201], v[42:45]
	v_mfma_f32_16x16x32_bf16 v[30:33], v[150:153], v[206:209], v[30:33]
	v_mfma_f32_16x16x32_bf16 v[26:29], v[164:167], v[206:209], v[26:29]
	v_mfma_f32_16x16x32_bf16 v[14:17], v[150:153], v[214:217], v[14:17]
	v_mfma_f32_16x16x32_bf16 v[10:13], v[164:167], v[214:217], v[10:13]
	v_mfma_f32_16x16x32_bf16 v[54:57], v[168:171], v[184:187], v[54:57]
	v_mfma_f32_16x16x32_bf16 v[50:53], v[176:179], v[184:187], v[50:53]
	v_mfma_f32_16x16x32_bf16 v[38:41], v[168:171], v[192:195], v[38:41]
	v_mfma_f32_16x16x32_bf16 v[34:37], v[176:179], v[192:195], v[34:37]
	v_mfma_f32_16x16x32_bf16 v[22:25], v[168:171], v[202:205], v[22:25]
	v_mfma_f32_16x16x32_bf16 v[18:21], v[176:179], v[202:205], v[18:21]
	v_mfma_f32_16x16x32_bf16 v[6:9], v[168:171], v[210:213], v[6:9]
	v_mfma_f32_16x16x32_bf16 v[2:5], v[176:179], v[210:213], v[2:5]
	v_mfma_f32_16x16x32_bf16 v[54:57], v[172:175], v[188:191], v[54:57]
	v_mfma_f32_16x16x32_bf16 v[50:53], v[180:183], v[188:191], v[50:53]
	v_mfma_f32_16x16x32_bf16 v[38:41], v[172:175], v[198:201], v[38:41]
	v_mfma_f32_16x16x32_bf16 v[34:37], v[180:183], v[198:201], v[34:37]
	v_mfma_f32_16x16x32_bf16 v[22:25], v[172:175], v[206:209], v[22:25]
	v_mfma_f32_16x16x32_bf16 v[18:21], v[180:183], v[206:209], v[18:21]
	v_mfma_f32_16x16x32_bf16 v[6:9], v[172:175], v[214:217], v[6:9]
	v_mfma_f32_16x16x32_bf16 v[2:5], v[180:183], v[214:217], v[2:5]
	s_barrier
	s_setprio 0
	s_add_i32 s68, 0, 0x18000
	s_add_i32 s69, 0, 0x1c000
	v_add_u32_e32 v164, s68, v154
	v_add_u32_e32 v180, s69, v154
	ds_read_b128 v[146:149], v164
	ds_read_b128 v[150:153], v164 offset:1024
	ds_read_b128 v[160:163], v164 offset:2048
	ds_read_b128 v[164:167], v164 offset:3072
	ds_read_b128 v[168:171], v180
	ds_read_b128 v[172:175], v180 offset:1024
	ds_read_b128 v[176:179], v180 offset:2048
	ds_read_b128 v[180:183], v180 offset:3072
	s_add_u32 s46, s46, 0x400000
	s_addc_u32 s47, s47, 0
	s_mov_b32 m0, s50
	ds_read_b128 v[184:187], v158 offset:32768
	ds_read_b128 v[188:191], v158 offset:33792
	ds_read_b128 v[192:195], v158 offset:34816
	ds_read_b128 v[198:201], v158 offset:35840
	ds_read_b128 v[202:205], v158 offset:36864
	ds_read_b128 v[206:209], v158 offset:37888
	ds_read_b128 v[210:213], v158 offset:38912
	ds_read_b128 v[214:217], v158 offset:39936
	global_load_lds_dwordx4 v130, s[46:47]
	s_mov_b32 m0, s51
	s_nop 0
	global_load_lds_dwordx4 v134, s[46:47]
	s_waitcnt vmcnt(8)
	s_waitcnt lgkmcnt(0)
	s_setprio 1
	s_barrier
	v_mfma_f32_16x16x32_bf16 v[126:129], v[146:149], v[184:187], v[126:129]
	v_mfma_f32_16x16x32_bf16 v[122:125], v[160:163], v[184:187], v[122:125]
	v_mfma_f32_16x16x32_bf16 v[110:113], v[146:149], v[192:195], v[110:113]
	v_mfma_f32_16x16x32_bf16 v[106:109], v[160:163], v[192:195], v[106:109]
	v_mfma_f32_16x16x32_bf16 v[94:97], v[146:149], v[202:205], v[94:97]
	v_mfma_f32_16x16x32_bf16 v[90:93], v[160:163], v[202:205], v[90:93]
	v_mfma_f32_16x16x32_bf16 v[78:81], v[146:149], v[210:213], v[78:81]
	v_mfma_f32_16x16x32_bf16 v[74:77], v[160:163], v[210:213], v[74:77]
	v_mfma_f32_16x16x32_bf16 v[126:129], v[150:153], v[188:191], v[126:129]
	v_mfma_f32_16x16x32_bf16 v[122:125], v[164:167], v[188:191], v[122:125]
	v_mfma_f32_16x16x32_bf16 v[110:113], v[150:153], v[198:201], v[110:113]
	v_mfma_f32_16x16x32_bf16 v[106:109], v[164:167], v[198:201], v[106:109]
	v_mfma_f32_16x16x32_bf16 v[94:97], v[150:153], v[206:209], v[94:97]
	v_mfma_f32_16x16x32_bf16 v[90:93], v[164:167], v[206:209], v[90:93]
	v_mfma_f32_16x16x32_bf16 v[78:81], v[150:153], v[214:217], v[78:81]
	v_mfma_f32_16x16x32_bf16 v[74:77], v[164:167], v[214:217], v[74:77]
	v_mfma_f32_16x16x32_bf16 v[118:121], v[168:171], v[184:187], v[118:121]
	v_mfma_f32_16x16x32_bf16 v[114:117], v[176:179], v[184:187], v[114:117]
	v_mfma_f32_16x16x32_bf16 v[102:105], v[168:171], v[192:195], v[102:105]
	v_mfma_f32_16x16x32_bf16 v[98:101], v[176:179], v[192:195], v[98:101]
	v_mfma_f32_16x16x32_bf16 v[86:89], v[168:171], v[202:205], v[86:89]
	v_mfma_f32_16x16x32_bf16 v[82:85], v[176:179], v[202:205], v[82:85]
	v_mfma_f32_16x16x32_bf16 v[70:73], v[168:171], v[210:213], v[70:73]
	v_mfma_f32_16x16x32_bf16 v[66:69], v[176:179], v[210:213], v[66:69]
	v_mfma_f32_16x16x32_bf16 v[118:121], v[172:175], v[188:191], v[118:121]
	v_mfma_f32_16x16x32_bf16 v[114:117], v[180:183], v[188:191], v[114:117]
	v_mfma_f32_16x16x32_bf16 v[102:105], v[172:175], v[198:201], v[102:105]
	v_mfma_f32_16x16x32_bf16 v[98:101], v[180:183], v[198:201], v[98:101]
	v_mfma_f32_16x16x32_bf16 v[86:89], v[172:175], v[206:209], v[86:89]
	v_mfma_f32_16x16x32_bf16 v[82:85], v[180:183], v[206:209], v[82:85]
	v_mfma_f32_16x16x32_bf16 v[70:73], v[172:175], v[214:217], v[70:73]
	v_mfma_f32_16x16x32_bf16 v[66:69], v[180:183], v[214:217], v[66:69]
	s_barrier
	s_setprio 0
	s_add_u32 s44, s44, 0x80
	s_addc_u32 s45, s45, 0
	s_add_u32 s68, s44, 0x400000
	s_addc_u32 s69, s45, 0
	s_add_u32 s46, s46, 0xffc00080
	s_addc_u32 s47, s47, -1
	s_add_i32 m0, s48, 0x18000
	ds_read_b128 v[184:187], v158 offset:49152
	global_load_lds_dwordx4 v132, s[44:45]
	s_add_i32 m0, s48, 0x1a000
	ds_read_b128 v[188:191], v158 offset:50176
	global_load_lds_dwordx4 v136, s[44:45]
	s_add_i32 m0, s48, 0x1c000
	ds_read_b128 v[192:195], v158 offset:51200
	global_load_lds_dwordx4 v132, s[68:69]
	s_add_i32 m0, s48, 0x1e000
	ds_read_b128 v[198:201], v158 offset:52224
	global_load_lds_dwordx4 v136, s[68:69]
	s_add_i32 m0, s48, 0x8000
	ds_read_b128 v[202:205], v158 offset:53248
	global_load_lds_dwordx4 v130, s[46:47]
	s_add_i32 m0, s48, 0xa000
	ds_read_b128 v[206:209], v158 offset:54272
	global_load_lds_dwordx4 v134, s[46:47]
	ds_read_b128 v[210:213], v158 offset:55296
	ds_read_b128 v[214:217], v158 offset:56320
	s_waitcnt vmcnt(8)
	s_waitcnt lgkmcnt(0)
	s_setprio 1
	s_barrier
	v_mfma_f32_16x16x32_bf16 v[62:65], v[146:149], v[184:187], v[62:65]
	v_mfma_f32_16x16x32_bf16 v[58:61], v[160:163], v[184:187], v[58:61]
	v_mfma_f32_16x16x32_bf16 v[46:49], v[146:149], v[192:195], v[46:49]
	v_mfma_f32_16x16x32_bf16 v[42:45], v[160:163], v[192:195], v[42:45]
	v_mfma_f32_16x16x32_bf16 v[30:33], v[146:149], v[202:205], v[30:33]
	v_mfma_f32_16x16x32_bf16 v[26:29], v[160:163], v[202:205], v[26:29]
	v_mfma_f32_16x16x32_bf16 v[14:17], v[146:149], v[210:213], v[14:17]
	v_mfma_f32_16x16x32_bf16 v[10:13], v[160:163], v[210:213], v[10:13]
	v_mfma_f32_16x16x32_bf16 v[62:65], v[150:153], v[188:191], v[62:65]
	v_mfma_f32_16x16x32_bf16 v[58:61], v[164:167], v[188:191], v[58:61]
	v_mfma_f32_16x16x32_bf16 v[46:49], v[150:153], v[198:201], v[46:49]
	v_mfma_f32_16x16x32_bf16 v[42:45], v[164:167], v[198:201], v[42:45]
	v_mfma_f32_16x16x32_bf16 v[30:33], v[150:153], v[206:209], v[30:33]
	v_mfma_f32_16x16x32_bf16 v[26:29], v[164:167], v[206:209], v[26:29]
	v_mfma_f32_16x16x32_bf16 v[14:17], v[150:153], v[214:217], v[14:17]
	v_mfma_f32_16x16x32_bf16 v[10:13], v[164:167], v[214:217], v[10:13]
	v_mfma_f32_16x16x32_bf16 v[54:57], v[168:171], v[184:187], v[54:57]
	v_mfma_f32_16x16x32_bf16 v[50:53], v[176:179], v[184:187], v[50:53]
	v_mfma_f32_16x16x32_bf16 v[38:41], v[168:171], v[192:195], v[38:41]
	v_mfma_f32_16x16x32_bf16 v[34:37], v[176:179], v[192:195], v[34:37]
	v_mfma_f32_16x16x32_bf16 v[22:25], v[168:171], v[202:205], v[22:25]
	v_mfma_f32_16x16x32_bf16 v[18:21], v[176:179], v[202:205], v[18:21]
	v_mfma_f32_16x16x32_bf16 v[6:9], v[168:171], v[210:213], v[6:9]
	v_mfma_f32_16x16x32_bf16 v[2:5], v[176:179], v[210:213], v[2:5]
	v_mfma_f32_16x16x32_bf16 v[54:57], v[172:175], v[188:191], v[54:57]
	v_mfma_f32_16x16x32_bf16 v[50:53], v[180:183], v[188:191], v[50:53]
	v_mfma_f32_16x16x32_bf16 v[38:41], v[172:175], v[198:201], v[38:41]
	v_mfma_f32_16x16x32_bf16 v[34:37], v[180:183], v[198:201], v[34:37]
	v_mfma_f32_16x16x32_bf16 v[22:25], v[172:175], v[206:209], v[22:25]
	v_mfma_f32_16x16x32_bf16 v[18:21], v[180:183], v[206:209], v[18:21]
	v_mfma_f32_16x16x32_bf16 v[6:9], v[172:175], v[214:217], v[6:9]
	v_mfma_f32_16x16x32_bf16 v[2:5], v[180:183], v[214:217], v[2:5]
	s_barrier
	s_setprio 0
	s_add_i32 s67, s67, 2
	s_add_u32 s42, s42, 0x100
	s_addc_u32 s43, s43, 0
	s_add_u32 s65, s65, 0x100
	s_addc_u32 s66, s66, 0
	s_cmpk_gt_u32 s67, 0xfd
	s_cbranch_scc0 .LBB0_897
	s_and_b64 vcc, exec, s[14:15]
	s_cbranch_vccz .LBB0_900
	s_barrier
